# EP1: hand-written in-proj epilogue fast paths (cat1 rope/plain, silu, transposed V through LDS)
# speedup vs baseline: 1.0099x; 1.0099x over previous
.LBB0_187:
	v_mov_b32_e32 v73, v156
	s_nop 15
	s_nop 7
	s_mov_b64 s[6:7], exec
	v_lshrrev_b32_e32 v77, 6, v156
	v_and_b32_e32 v66, 63, v156
	v_readfirstlane_b32 s4, v77
	s_and_b32 s5, s4, 1
	s_lshr_b32 s8, s4, 1
	s_lshl_b32 s9, s44, 1
	s_add_u32 s9, s9, s5
	s_cmp_gt_u32 s9, 59
	s_cbranch_scc1 .Lep_orig
	s_cmp_lt_u32 s9, 4
	s_cbranch_scc0 .Lep_g0_no
	s_movk_i32 s10, 122
	s_movk_i32 s11, 0
	s_movk_i32 s12, 2
	s_movk_i32 s13, 0
	s_mov_b32 s14, 0x3e38aa3b
	s_movk_i32 s15, 1
	s_branch .Lep_decoded
.Lep_g0_no:
	s_cmp_lt_u32 s9, 8
	s_cbranch_scc0 .Lep_g1_no
	s_movk_i32 s10, 130
	s_movk_i32 s11, 4
	s_movk_i32 s12, 2
	s_movk_i32 s13, 0
	s_mov_b32 s14, 0x3f800000
	s_movk_i32 s15, 0
	s_branch .Lep_decoded
.Lep_g1_no:
	s_cmp_lt_u32 s9, 12
	s_cbranch_scc0 .Lep_g2_no
	s_movk_i32 s10, 138
	s_movk_i32 s11, 8
	s_movk_i32 s12, 2
	s_movk_i32 s13, 4
	s_mov_b32 s14, 0x3f800000
	s_movk_i32 s15, 0
	s_branch .Lep_decoded
.Lep_g2_no:
	s_cmp_lt_u32 s9, 16
	s_cbranch_scc0 .Lep_g3_no
	s_movk_i32 s10, 0
	s_movk_i32 s11, 12
	s_movk_i32 s12, 0
	s_movk_i32 s13, 3
	s_mov_b32 s14, 0x3f800000
	s_movk_i32 s15, 0
	s_branch .Lep_decoded
.Lep_g3_no:
	s_cmp_lt_u32 s9, 24
	s_cbranch_scc0 .Lep_g4_no
	s_movk_i32 s10, 146
	s_movk_i32 s11, 16
	s_movk_i32 s12, 3
	s_movk_i32 s13, 1
	s_mov_b32 s14, 0x3e38aa3b
	s_movk_i32 s15, 1
	s_branch .Lep_decoded
.Lep_g4_no:
	s_cmp_lt_u32 s9, 26
	s_cbranch_scc0 .Lep_g5_no
	s_movk_i32 s10, 162
	s_movk_i32 s11, 24
	s_movk_i32 s12, 1
	s_movk_i32 s13, 1
	s_mov_b32 s14, 0x3f800000
	s_movk_i32 s15, 0
	s_branch .Lep_decoded
.Lep_g5_no:
	s_cmp_lt_u32 s9, 28
	s_cbranch_scc0 .Lep_g6_no
	s_movk_i32 s10, 166
	s_movk_i32 s11, 26
	s_movk_i32 s12, 1
	s_movk_i32 s13, 0
	s_mov_b32 s14, 0x3f800000
	s_movk_i32 s15, 0
	s_branch .Lep_decoded
.Lep_g6_no:
	s_cmp_lt_u32 s9, 30
	s_cbranch_scc0 .Lep_g7_no
	s_movk_i32 s10, 170
	s_movk_i32 s11, 28
	s_movk_i32 s12, 1
	s_movk_i32 s13, 1
	s_mov_b32 s14, 0x3f800000
	s_movk_i32 s15, 0
	s_branch .Lep_decoded
.Lep_g7_no:
	s_cmp_lt_u32 s9, 32
	s_cbranch_scc0 .Lep_g8_no
	s_movk_i32 s10, 174
	s_movk_i32 s11, 30
	s_movk_i32 s12, 1
	s_movk_i32 s13, 4
	s_mov_b32 s14, 0x3f800000
	s_movk_i32 s15, 0
	s_branch .Lep_decoded
.Lep_g8_no:
	s_cmp_lt_u32 s9, 34
	s_cbranch_scc0 .Lep_g9_no
	s_movk_i32 s10, 178
	s_movk_i32 s11, 32
	s_movk_i32 s12, 1
	s_movk_i32 s13, 1
	s_mov_b32 s14, 0x3f800000
	s_movk_i32 s15, 0
	s_branch .Lep_decoded
.Lep_g9_no:
	s_cmp_lt_u32 s9, 36
	s_cbranch_scc0 .Lep_g10_no
	s_movk_i32 s10, 182
	s_movk_i32 s11, 34
	s_movk_i32 s12, 1
	s_movk_i32 s13, 4
	s_mov_b32 s14, 0x3f800000
	s_movk_i32 s15, 0
	s_branch .Lep_decoded
.Lep_g10_no:
	s_cmp_lt_u32 s9, 44
	s_cbranch_scc0 .Lep_g11_no
	s_movk_i32 s10, 256
	s_movk_i32 s11, 36
	s_movk_i32 s12, 0
	s_movk_i32 s13, 3
	s_mov_b32 s14, 0x3f800000
	s_movk_i32 s15, 0
	s_branch .Lep_decoded
.Lep_g11_no:
	s_cmp_lt_u32 s9, 48
	s_cbranch_scc0 .Lep_g12_no
	s_movk_i32 s10, 186
	s_movk_i32 s11, 44
	s_movk_i32 s12, 2
	s_movk_i32 s13, 2
	s_mov_b32 s14, 0x3e8293ee
	s_movk_i32 s15, 1
	s_branch .Lep_decoded
.Lep_g12_no:
	s_cmp_lt_u32 s9, 52
	s_cbranch_scc0 .Lep_g13_no
	s_movk_i32 s10, 194
	s_movk_i32 s11, 48
	s_movk_i32 s12, 2
	s_movk_i32 s13, 2
	s_mov_b32 s14, 0x3f800000
	s_movk_i32 s15, 0
	s_branch .Lep_decoded
.Lep_g13_no:
	s_cmp_lt_u32 s9, 56
	s_cbranch_scc0 .Lep_g14_no
	s_movk_i32 s10, 202
	s_movk_i32 s11, 52
	s_movk_i32 s12, 2
	s_movk_i32 s13, 4
	s_mov_b32 s14, 0x3f800000
	s_movk_i32 s15, 0
	s_branch .Lep_decoded
.Lep_g14_no:
	s_cmp_lt_u32 s9, 60
	s_cbranch_scc0 .Lep_g15_no
	s_movk_i32 s10, 768
	s_movk_i32 s11, 56
	s_movk_i32 s12, 0
	s_movk_i32 s13, 3
	s_mov_b32 s14, 0x3f800000
	s_movk_i32 s15, 0
	s_branch .Lep_decoded
.Lep_g15_no:
.Lep_decoded:
	s_sub_u32 s16, s9, s11
	s_lshr_b32 s17, s0, 6
	s_lshl_b32 s17, s17, s12
	s_add_u32 s17, s17, s16
	s_and_b32 s26, s0, 63
	s_lshl_b32 s26, s26, 7
	s_lshl_b32 s27, s8, 6
	s_add_u32 s26, s26, s27
	v_and_b32_e32 v67, 31, v66
	v_lshrrev_b32_e32 v68, 5, v66
	s_mul_i32 s72, s4, 0x2400
	v_lshrrev_b32_e32 v77, 3, v66
	v_and_b32_e32 v78, 7, v66
	v_mul_u32_u24_e32 v74, 0x90, v77
	v_lshl_add_u32 v74, v78, 4, v74
	v_add_u32_e32 v74, s72, v74
	s_cmp_eq_u32 s13, 4
	s_cbranch_scc1 .Lep_cat2
	s_cmp_eq_u32 s13, 3
	s_cbranch_scc1 .Lep_cat3
	s_add_u32 s10, s10, s17
	s_lshl_b32 s73, s10, 20
	s_lshr_b32 s84, s10, 12
	s_add_u32 s10, s80, s73
	s_addc_u32 s11, s81, s84
	s_lshl_b32 s73, s26, 7
	s_add_u32 s10, s10, s73
	s_addc_u32 s11, s11, 0
	v_lshlrev_b32_e32 v75, 4, v66
	v_mul_u32_u24_e32 v69, 0x240, v68
	v_add_u32_e32 v69, s72, v69
	v_cvt_f32_u32_e32 v72, v68
	v_mov_b32_e32 v76, s14
	s_cmp_eq_u32 s13, 2
	s_cbranch_scc1 .Lep_c1_r2setup
	v_lshl_add_u32 v69, v67, 1, v69
	v_add_u32_e32 v70, 64, v69
	v_cvt_f32_u32_e32 v71, v67
	v_mul_f32_e32 v71, 0xbed49a78, v71
	s_branch .Lep_c1_setup_done
.Lep_c1_r2setup:
	v_and_b32_e32 v77, 15, v67
	v_lshrrev_b32_e32 v78, 4, v67
	v_lshl_add_u32 v78, v78, 5, v77
	v_lshl_add_u32 v69, v78, 1, v69
	v_add_u32_e32 v70, 32, v69
	v_cvt_f32_u32_e32 v71, v77
	v_mul_f32_e32 v71, 0xbf549a78, v71
.Lep_c1_setup_done:
	v_exp_f32_e32 v71, v71
	v_cvt_f32_u32_e32 v77, s26
	v_mul_f32_e32 v72, 4.0, v72
	v_mul_f32_e32 v71, 0.15915494, v71
	v_add_f32_e32 v72, v77, v72
	s_cmp_eq_u32 s13, 0
	s_cbranch_scc1 .Lep_c1_norope
	s_cmp_eq_u32 s15, 0
	s_cbranch_scc1 .Lep_c1_rope_ns
	v_add_f32_e32 v77, 0x00000000, v72
	v_add_f32_e32 v78, 0x3f800000, v72
	v_mul_f32_e32 v77, v77, v71
	v_mul_f32_e32 v78, v78, v71
	v_fract_f32_e32 v77, v77
	v_fract_f32_e32 v78, v78
	v_sin_f32_e32 v79, v77
	v_sin_f32_e32 v80, v78
	v_cos_f32_e32 v81, v77
	v_cos_f32_e32 v82, v78
	v_mul_f32_e32 v83, v18, v81
	v_mul_f32_e32 v84, v19, v82
	v_mul_f32_e32 v85, v50, v81
	v_mul_f32_e32 v86, v51, v82
	v_fma_f32 v83, -v50, v79, v83
	v_fma_f32 v84, -v51, v80, v84
	v_fmac_f32_e32 v85, v18, v79
	v_fmac_f32_e32 v86, v19, v80
	v_mul_f32_e32 v83, v83, v76
	v_mul_f32_e32 v84, v84, v76
	v_mul_f32_e32 v85, v85, v76
	v_mul_f32_e32 v86, v86, v76
	v_cvt_pk_bf16_f32 v83, v83, v84
	v_cvt_pk_bf16_f32 v85, v85, v86
	ds_write_b16 v69, v83 offset:0
	ds_write_b16_d16_hi v69, v83 offset:144
	ds_write_b16 v70, v85 offset:0
	ds_write_b16_d16_hi v70, v85 offset:144
	v_add_f32_e32 v77, 0x40000000, v72
	v_add_f32_e32 v78, 0x40400000, v72
	v_mul_f32_e32 v77, v77, v71
	v_mul_f32_e32 v78, v78, v71
	v_fract_f32_e32 v77, v77
	v_fract_f32_e32 v78, v78
	v_sin_f32_e32 v79, v77
	v_sin_f32_e32 v80, v78
	v_cos_f32_e32 v81, v77
	v_cos_f32_e32 v82, v78
	v_mul_f32_e32 v83, v20, v81
	v_mul_f32_e32 v84, v21, v82
	v_mul_f32_e32 v85, v52, v81
	v_mul_f32_e32 v86, v53, v82
	v_fma_f32 v83, -v52, v79, v83
	v_fma_f32 v84, -v53, v80, v84
	v_fmac_f32_e32 v85, v20, v79
	v_fmac_f32_e32 v86, v21, v80
	v_mul_f32_e32 v83, v83, v76
	v_mul_f32_e32 v84, v84, v76
	v_mul_f32_e32 v85, v85, v76
	v_mul_f32_e32 v86, v86, v76
	v_cvt_pk_bf16_f32 v83, v83, v84
	v_cvt_pk_bf16_f32 v85, v85, v86
	ds_write_b16 v69, v83 offset:288
	ds_write_b16_d16_hi v69, v83 offset:432
	ds_write_b16 v70, v85 offset:288
	ds_write_b16_d16_hi v70, v85 offset:432
	v_add_f32_e32 v77, 0x41000000, v72
	v_add_f32_e32 v78, 0x41100000, v72
	v_mul_f32_e32 v77, v77, v71
	v_mul_f32_e32 v78, v78, v71
	v_fract_f32_e32 v77, v77
	v_fract_f32_e32 v78, v78
	v_sin_f32_e32 v79, v77
	v_sin_f32_e32 v80, v78
	v_cos_f32_e32 v81, v77
	v_cos_f32_e32 v82, v78
	v_mul_f32_e32 v83, v22, v81
	v_mul_f32_e32 v84, v23, v82
	v_mul_f32_e32 v85, v54, v81
	v_mul_f32_e32 v86, v55, v82
	v_fma_f32 v83, -v54, v79, v83
	v_fma_f32 v84, -v55, v80, v84
	v_fmac_f32_e32 v85, v22, v79
	v_fmac_f32_e32 v86, v23, v80
	v_mul_f32_e32 v83, v83, v76
	v_mul_f32_e32 v84, v84, v76
	v_mul_f32_e32 v85, v85, v76
	v_mul_f32_e32 v86, v86, v76
	v_cvt_pk_bf16_f32 v83, v83, v84
	v_cvt_pk_bf16_f32 v85, v85, v86
	ds_write_b16 v69, v83 offset:1152
	ds_write_b16_d16_hi v69, v83 offset:1296
	ds_write_b16 v70, v85 offset:1152
	ds_write_b16_d16_hi v70, v85 offset:1296
	v_add_f32_e32 v77, 0x41200000, v72
	v_add_f32_e32 v78, 0x41300000, v72
	v_mul_f32_e32 v77, v77, v71
	v_mul_f32_e32 v78, v78, v71
	v_fract_f32_e32 v77, v77
	v_fract_f32_e32 v78, v78
	v_sin_f32_e32 v79, v77
	v_sin_f32_e32 v80, v78
	v_cos_f32_e32 v81, v77
	v_cos_f32_e32 v82, v78
	v_mul_f32_e32 v83, v24, v81
	v_mul_f32_e32 v84, v25, v82
	v_mul_f32_e32 v85, v56, v81
	v_mul_f32_e32 v86, v57, v82
	v_fma_f32 v83, -v56, v79, v83
	v_fma_f32 v84, -v57, v80, v84
	v_fmac_f32_e32 v85, v24, v79
	v_fmac_f32_e32 v86, v25, v80
	v_mul_f32_e32 v83, v83, v76
	v_mul_f32_e32 v84, v84, v76
	v_mul_f32_e32 v85, v85, v76
	v_mul_f32_e32 v86, v86, v76
	v_cvt_pk_bf16_f32 v83, v83, v84
	v_cvt_pk_bf16_f32 v85, v85, v86
	ds_write_b16 v69, v83 offset:1440
	ds_write_b16_d16_hi v69, v83 offset:1584
	ds_write_b16 v70, v85 offset:1440
	ds_write_b16_d16_hi v70, v85 offset:1584
	v_add_f32_e32 v77, 0x41800000, v72
	v_add_f32_e32 v78, 0x41880000, v72
	v_mul_f32_e32 v77, v77, v71
	v_mul_f32_e32 v78, v78, v71
	v_fract_f32_e32 v77, v77
	v_fract_f32_e32 v78, v78
	v_sin_f32_e32 v79, v77
	v_sin_f32_e32 v80, v78
	v_cos_f32_e32 v81, v77
	v_cos_f32_e32 v82, v78
	v_mul_f32_e32 v83, v26, v81
	v_mul_f32_e32 v84, v27, v82
	v_mul_f32_e32 v85, v58, v81
	v_mul_f32_e32 v86, v59, v82
	v_fma_f32 v83, -v58, v79, v83
	v_fma_f32 v84, -v59, v80, v84
	v_fmac_f32_e32 v85, v26, v79
	v_fmac_f32_e32 v86, v27, v80
	v_mul_f32_e32 v83, v83, v76
	v_mul_f32_e32 v84, v84, v76
	v_mul_f32_e32 v85, v85, v76
	v_mul_f32_e32 v86, v86, v76
	v_cvt_pk_bf16_f32 v83, v83, v84
	v_cvt_pk_bf16_f32 v85, v85, v86
	ds_write_b16 v69, v83 offset:2304
	ds_write_b16_d16_hi v69, v83 offset:2448
	ds_write_b16 v70, v85 offset:2304
	ds_write_b16_d16_hi v70, v85 offset:2448
	v_add_f32_e32 v77, 0x41900000, v72
	v_add_f32_e32 v78, 0x41980000, v72
	v_mul_f32_e32 v77, v77, v71
	v_mul_f32_e32 v78, v78, v71
	v_fract_f32_e32 v77, v77
	v_fract_f32_e32 v78, v78
	v_sin_f32_e32 v79, v77
	v_sin_f32_e32 v80, v78
	v_cos_f32_e32 v81, v77
	v_cos_f32_e32 v82, v78
	v_mul_f32_e32 v83, v28, v81
	v_mul_f32_e32 v84, v29, v82
	v_mul_f32_e32 v85, v60, v81
	v_mul_f32_e32 v86, v61, v82
	v_fma_f32 v83, -v60, v79, v83
	v_fma_f32 v84, -v61, v80, v84
	v_fmac_f32_e32 v85, v28, v79
	v_fmac_f32_e32 v86, v29, v80
	v_mul_f32_e32 v83, v83, v76
	v_mul_f32_e32 v84, v84, v76
	v_mul_f32_e32 v85, v85, v76
	v_mul_f32_e32 v86, v86, v76
	v_cvt_pk_bf16_f32 v83, v83, v84
	v_cvt_pk_bf16_f32 v85, v85, v86
	ds_write_b16 v69, v83 offset:2592
	ds_write_b16_d16_hi v69, v83 offset:2736
	ds_write_b16 v70, v85 offset:2592
	ds_write_b16_d16_hi v70, v85 offset:2736
	v_add_f32_e32 v77, 0x41c00000, v72
	v_add_f32_e32 v78, 0x41c80000, v72
	v_mul_f32_e32 v77, v77, v71
	v_mul_f32_e32 v78, v78, v71
	v_fract_f32_e32 v77, v77
	v_fract_f32_e32 v78, v78
	v_sin_f32_e32 v79, v77
	v_sin_f32_e32 v80, v78
	v_cos_f32_e32 v81, v77
	v_cos_f32_e32 v82, v78
	v_mul_f32_e32 v83, v30, v81
	v_mul_f32_e32 v84, v31, v82
	v_mul_f32_e32 v85, v62, v81
	v_mul_f32_e32 v86, v63, v82
	v_fma_f32 v83, -v62, v79, v83
	v_fma_f32 v84, -v63, v80, v84
	v_fmac_f32_e32 v85, v30, v79
	v_fmac_f32_e32 v86, v31, v80
	v_mul_f32_e32 v83, v83, v76
	v_mul_f32_e32 v84, v84, v76
	v_mul_f32_e32 v85, v85, v76
	v_mul_f32_e32 v86, v86, v76
	v_cvt_pk_bf16_f32 v83, v83, v84
	v_cvt_pk_bf16_f32 v85, v85, v86
	ds_write_b16 v69, v83 offset:3456
	ds_write_b16_d16_hi v69, v83 offset:3600
	ds_write_b16 v70, v85 offset:3456
	ds_write_b16_d16_hi v70, v85 offset:3600
	v_add_f32_e32 v77, 0x41d00000, v72
	v_add_f32_e32 v78, 0x41d80000, v72
	v_mul_f32_e32 v77, v77, v71
	v_mul_f32_e32 v78, v78, v71
	v_fract_f32_e32 v77, v77
	v_fract_f32_e32 v78, v78
	v_sin_f32_e32 v79, v77
	v_sin_f32_e32 v80, v78
	v_cos_f32_e32 v81, v77
	v_cos_f32_e32 v82, v78
	v_mul_f32_e32 v83, v32, v81
	v_mul_f32_e32 v84, v33, v82
	v_mul_f32_e32 v85, v64, v81
	v_mul_f32_e32 v86, v65, v82
	v_fma_f32 v83, -v64, v79, v83
	v_fma_f32 v84, -v65, v80, v84
	v_fmac_f32_e32 v85, v32, v79
	v_fmac_f32_e32 v86, v33, v80
	v_mul_f32_e32 v83, v83, v76
	v_mul_f32_e32 v84, v84, v76
	v_mul_f32_e32 v85, v85, v76
	v_mul_f32_e32 v86, v86, v76
	v_cvt_pk_bf16_f32 v83, v83, v84
	v_cvt_pk_bf16_f32 v85, v85, v86
	ds_write_b16 v69, v83 offset:3744
	ds_write_b16_d16_hi v69, v83 offset:3888
	ds_write_b16 v70, v85 offset:3744
	ds_write_b16_d16_hi v70, v85 offset:3888
	v_add_f32_e32 v77, 0x42000000, v72
	v_add_f32_e32 v78, 0x42040000, v72
	v_mul_f32_e32 v77, v77, v71
	v_mul_f32_e32 v78, v78, v71
	v_fract_f32_e32 v77, v77
	v_fract_f32_e32 v78, v78
	v_sin_f32_e32 v79, v77
	v_sin_f32_e32 v80, v78
	v_cos_f32_e32 v81, v77
	v_cos_f32_e32 v82, v78
	v_mul_f32_e32 v83, v2, v81
	v_mul_f32_e32 v84, v3, v82
	v_mul_f32_e32 v85, v34, v81
	v_mul_f32_e32 v86, v35, v82
	v_fma_f32 v83, -v34, v79, v83
	v_fma_f32 v84, -v35, v80, v84
	v_fmac_f32_e32 v85, v2, v79
	v_fmac_f32_e32 v86, v3, v80
	v_mul_f32_e32 v83, v83, v76
	v_mul_f32_e32 v84, v84, v76
	v_mul_f32_e32 v85, v85, v76
	v_mul_f32_e32 v86, v86, v76
	v_cvt_pk_bf16_f32 v83, v83, v84
	v_cvt_pk_bf16_f32 v85, v85, v86
	ds_write_b16 v69, v83 offset:4608
	ds_write_b16_d16_hi v69, v83 offset:4752
	ds_write_b16 v70, v85 offset:4608
	ds_write_b16_d16_hi v70, v85 offset:4752
	v_add_f32_e32 v77, 0x42080000, v72
	v_add_f32_e32 v78, 0x420c0000, v72
	v_mul_f32_e32 v77, v77, v71
	v_mul_f32_e32 v78, v78, v71
	v_fract_f32_e32 v77, v77
	v_fract_f32_e32 v78, v78
	v_sin_f32_e32 v79, v77
	v_sin_f32_e32 v80, v78
	v_cos_f32_e32 v81, v77
	v_cos_f32_e32 v82, v78
	v_mul_f32_e32 v83, v4, v81
	v_mul_f32_e32 v84, v5, v82
	v_mul_f32_e32 v85, v36, v81
	v_mul_f32_e32 v86, v37, v82
	v_fma_f32 v83, -v36, v79, v83
	v_fma_f32 v84, -v37, v80, v84
	v_fmac_f32_e32 v85, v4, v79
	v_fmac_f32_e32 v86, v5, v80
	v_mul_f32_e32 v83, v83, v76
	v_mul_f32_e32 v84, v84, v76
	v_mul_f32_e32 v85, v85, v76
	v_mul_f32_e32 v86, v86, v76
	v_cvt_pk_bf16_f32 v83, v83, v84
	v_cvt_pk_bf16_f32 v85, v85, v86
	ds_write_b16 v69, v83 offset:4896
	ds_write_b16_d16_hi v69, v83 offset:5040
	ds_write_b16 v70, v85 offset:4896
	ds_write_b16_d16_hi v70, v85 offset:5040
	v_add_f32_e32 v77, 0x42200000, v72
	v_add_f32_e32 v78, 0x42240000, v72
	v_mul_f32_e32 v77, v77, v71
	v_mul_f32_e32 v78, v78, v71
	v_fract_f32_e32 v77, v77
	v_fract_f32_e32 v78, v78
	v_sin_f32_e32 v79, v77
	v_sin_f32_e32 v80, v78
	v_cos_f32_e32 v81, v77
	v_cos_f32_e32 v82, v78
	v_mul_f32_e32 v83, v6, v81
	v_mul_f32_e32 v84, v7, v82
	v_mul_f32_e32 v85, v38, v81
	v_mul_f32_e32 v86, v39, v82
	v_fma_f32 v83, -v38, v79, v83
	v_fma_f32 v84, -v39, v80, v84
	v_fmac_f32_e32 v85, v6, v79
	v_fmac_f32_e32 v86, v7, v80
	v_mul_f32_e32 v83, v83, v76
	v_mul_f32_e32 v84, v84, v76
	v_mul_f32_e32 v85, v85, v76
	v_mul_f32_e32 v86, v86, v76
	v_cvt_pk_bf16_f32 v83, v83, v84
	v_cvt_pk_bf16_f32 v85, v85, v86
	ds_write_b16 v69, v83 offset:5760
	ds_write_b16_d16_hi v69, v83 offset:5904
	ds_write_b16 v70, v85 offset:5760
	ds_write_b16_d16_hi v70, v85 offset:5904
	v_add_f32_e32 v77, 0x42280000, v72
	v_add_f32_e32 v78, 0x422c0000, v72
	v_mul_f32_e32 v77, v77, v71
	v_mul_f32_e32 v78, v78, v71
	v_fract_f32_e32 v77, v77
	v_fract_f32_e32 v78, v78
	v_sin_f32_e32 v79, v77
	v_sin_f32_e32 v80, v78
	v_cos_f32_e32 v81, v77
	v_cos_f32_e32 v82, v78
	v_mul_f32_e32 v83, v8, v81
	v_mul_f32_e32 v84, v9, v82
	v_mul_f32_e32 v85, v40, v81
	v_mul_f32_e32 v86, v41, v82
	v_fma_f32 v83, -v40, v79, v83
	v_fma_f32 v84, -v41, v80, v84
	v_fmac_f32_e32 v85, v8, v79
	v_fmac_f32_e32 v86, v9, v80
	v_mul_f32_e32 v83, v83, v76
	v_mul_f32_e32 v84, v84, v76
	v_mul_f32_e32 v85, v85, v76
	v_mul_f32_e32 v86, v86, v76
	v_cvt_pk_bf16_f32 v83, v83, v84
	v_cvt_pk_bf16_f32 v85, v85, v86
	ds_write_b16 v69, v83 offset:6048
	ds_write_b16_d16_hi v69, v83 offset:6192
	ds_write_b16 v70, v85 offset:6048
	ds_write_b16_d16_hi v70, v85 offset:6192
	v_add_f32_e32 v77, 0x42400000, v72
	v_add_f32_e32 v78, 0x42440000, v72
	v_mul_f32_e32 v77, v77, v71
	v_mul_f32_e32 v78, v78, v71
	v_fract_f32_e32 v77, v77
	v_fract_f32_e32 v78, v78
	v_sin_f32_e32 v79, v77
	v_sin_f32_e32 v80, v78
	v_cos_f32_e32 v81, v77
	v_cos_f32_e32 v82, v78
	v_mul_f32_e32 v83, v10, v81
	v_mul_f32_e32 v84, v11, v82
	v_mul_f32_e32 v85, v42, v81
	v_mul_f32_e32 v86, v43, v82
	v_fma_f32 v83, -v42, v79, v83
	v_fma_f32 v84, -v43, v80, v84
	v_fmac_f32_e32 v85, v10, v79
	v_fmac_f32_e32 v86, v11, v80
	v_mul_f32_e32 v83, v83, v76
	v_mul_f32_e32 v84, v84, v76
	v_mul_f32_e32 v85, v85, v76
	v_mul_f32_e32 v86, v86, v76
	v_cvt_pk_bf16_f32 v83, v83, v84
	v_cvt_pk_bf16_f32 v85, v85, v86
	ds_write_b16 v69, v83 offset:6912
	ds_write_b16_d16_hi v69, v83 offset:7056
	ds_write_b16 v70, v85 offset:6912
	ds_write_b16_d16_hi v70, v85 offset:7056
	v_add_f32_e32 v77, 0x42480000, v72
	v_add_f32_e32 v78, 0x424c0000, v72
	v_mul_f32_e32 v77, v77, v71
	v_mul_f32_e32 v78, v78, v71
	v_fract_f32_e32 v77, v77
	v_fract_f32_e32 v78, v78
	v_sin_f32_e32 v79, v77
	v_sin_f32_e32 v80, v78
	v_cos_f32_e32 v81, v77
	v_cos_f32_e32 v82, v78
	v_mul_f32_e32 v83, v12, v81
	v_mul_f32_e32 v84, v13, v82
	v_mul_f32_e32 v85, v44, v81
	v_mul_f32_e32 v86, v45, v82
	v_fma_f32 v83, -v44, v79, v83
	v_fma_f32 v84, -v45, v80, v84
	v_fmac_f32_e32 v85, v12, v79
	v_fmac_f32_e32 v86, v13, v80
	v_mul_f32_e32 v83, v83, v76
	v_mul_f32_e32 v84, v84, v76
	v_mul_f32_e32 v85, v85, v76
	v_mul_f32_e32 v86, v86, v76
	v_cvt_pk_bf16_f32 v83, v83, v84
	v_cvt_pk_bf16_f32 v85, v85, v86
	ds_write_b16 v69, v83 offset:7200
	ds_write_b16_d16_hi v69, v83 offset:7344
	ds_write_b16 v70, v85 offset:7200
	ds_write_b16_d16_hi v70, v85 offset:7344
	v_add_f32_e32 v77, 0x42600000, v72
	v_add_f32_e32 v78, 0x42640000, v72
	v_mul_f32_e32 v77, v77, v71
	v_mul_f32_e32 v78, v78, v71
	v_fract_f32_e32 v77, v77
	v_fract_f32_e32 v78, v78
	v_sin_f32_e32 v79, v77
	v_sin_f32_e32 v80, v78
	v_cos_f32_e32 v81, v77
	v_cos_f32_e32 v82, v78
	v_mul_f32_e32 v83, v14, v81
	v_mul_f32_e32 v84, v15, v82
	v_mul_f32_e32 v85, v46, v81
	v_mul_f32_e32 v86, v47, v82
	v_fma_f32 v83, -v46, v79, v83
	v_fma_f32 v84, -v47, v80, v84
	v_fmac_f32_e32 v85, v14, v79
	v_fmac_f32_e32 v86, v15, v80
	v_mul_f32_e32 v83, v83, v76
	v_mul_f32_e32 v84, v84, v76
	v_mul_f32_e32 v85, v85, v76
	v_mul_f32_e32 v86, v86, v76
	v_cvt_pk_bf16_f32 v83, v83, v84
	v_cvt_pk_bf16_f32 v85, v85, v86
	ds_write_b16 v69, v83 offset:8064
	ds_write_b16_d16_hi v69, v83 offset:8208
	ds_write_b16 v70, v85 offset:8064
	ds_write_b16_d16_hi v70, v85 offset:8208
	v_add_f32_e32 v77, 0x42680000, v72
	v_add_f32_e32 v78, 0x426c0000, v72
	v_mul_f32_e32 v77, v77, v71
	v_mul_f32_e32 v78, v78, v71
	v_fract_f32_e32 v77, v77
	v_fract_f32_e32 v78, v78
	v_sin_f32_e32 v79, v77
	v_sin_f32_e32 v80, v78
	v_cos_f32_e32 v81, v77
	v_cos_f32_e32 v82, v78
	v_mul_f32_e32 v83, v16, v81
	v_mul_f32_e32 v84, v17, v82
	v_mul_f32_e32 v85, v48, v81
	v_mul_f32_e32 v86, v49, v82
	v_fma_f32 v83, -v48, v79, v83
	v_fma_f32 v84, -v49, v80, v84
	v_fmac_f32_e32 v85, v16, v79
	v_fmac_f32_e32 v86, v17, v80
	v_mul_f32_e32 v83, v83, v76
	v_mul_f32_e32 v84, v84, v76
	v_mul_f32_e32 v85, v85, v76
	v_mul_f32_e32 v86, v86, v76
	v_cvt_pk_bf16_f32 v83, v83, v84
	v_cvt_pk_bf16_f32 v85, v85, v86
	ds_write_b16 v69, v83 offset:8352
	ds_write_b16_d16_hi v69, v83 offset:8496
	ds_write_b16 v70, v85 offset:8352
	ds_write_b16_d16_hi v70, v85 offset:8496
	s_branch .Lep_rowstore
.Lep_c1_rope_ns:
	v_add_f32_e32 v77, 0x00000000, v72
	v_add_f32_e32 v78, 0x3f800000, v72
	v_mul_f32_e32 v77, v77, v71
	v_mul_f32_e32 v78, v78, v71
	v_fract_f32_e32 v77, v77
	v_fract_f32_e32 v78, v78
	v_sin_f32_e32 v79, v77
	v_sin_f32_e32 v80, v78
	v_cos_f32_e32 v81, v77
	v_cos_f32_e32 v82, v78
	v_mul_f32_e32 v83, v18, v81
	v_mul_f32_e32 v84, v19, v82
	v_mul_f32_e32 v85, v50, v81
	v_mul_f32_e32 v86, v51, v82
	v_fma_f32 v83, -v50, v79, v83
	v_fma_f32 v84, -v51, v80, v84
	v_fmac_f32_e32 v85, v18, v79
	v_fmac_f32_e32 v86, v19, v80
	v_cvt_pk_bf16_f32 v83, v83, v84
	v_cvt_pk_bf16_f32 v85, v85, v86
	ds_write_b16 v69, v83 offset:0
	ds_write_b16_d16_hi v69, v83 offset:144
	ds_write_b16 v70, v85 offset:0
	ds_write_b16_d16_hi v70, v85 offset:144
	v_add_f32_e32 v77, 0x40000000, v72
	v_add_f32_e32 v78, 0x40400000, v72
	v_mul_f32_e32 v77, v77, v71
	v_mul_f32_e32 v78, v78, v71
	v_fract_f32_e32 v77, v77
	v_fract_f32_e32 v78, v78
	v_sin_f32_e32 v79, v77
	v_sin_f32_e32 v80, v78
	v_cos_f32_e32 v81, v77
	v_cos_f32_e32 v82, v78
	v_mul_f32_e32 v83, v20, v81
	v_mul_f32_e32 v84, v21, v82
	v_mul_f32_e32 v85, v52, v81
	v_mul_f32_e32 v86, v53, v82
	v_fma_f32 v83, -v52, v79, v83
	v_fma_f32 v84, -v53, v80, v84
	v_fmac_f32_e32 v85, v20, v79
	v_fmac_f32_e32 v86, v21, v80
	v_cvt_pk_bf16_f32 v83, v83, v84
	v_cvt_pk_bf16_f32 v85, v85, v86
	ds_write_b16 v69, v83 offset:288
	ds_write_b16_d16_hi v69, v83 offset:432
	ds_write_b16 v70, v85 offset:288
	ds_write_b16_d16_hi v70, v85 offset:432
	v_add_f32_e32 v77, 0x41000000, v72
	v_add_f32_e32 v78, 0x41100000, v72
	v_mul_f32_e32 v77, v77, v71
	v_mul_f32_e32 v78, v78, v71
	v_fract_f32_e32 v77, v77
	v_fract_f32_e32 v78, v78
	v_sin_f32_e32 v79, v77
	v_sin_f32_e32 v80, v78
	v_cos_f32_e32 v81, v77
	v_cos_f32_e32 v82, v78
	v_mul_f32_e32 v83, v22, v81
	v_mul_f32_e32 v84, v23, v82
	v_mul_f32_e32 v85, v54, v81
	v_mul_f32_e32 v86, v55, v82
	v_fma_f32 v83, -v54, v79, v83
	v_fma_f32 v84, -v55, v80, v84
	v_fmac_f32_e32 v85, v22, v79
	v_fmac_f32_e32 v86, v23, v80
	v_cvt_pk_bf16_f32 v83, v83, v84
	v_cvt_pk_bf16_f32 v85, v85, v86
	ds_write_b16 v69, v83 offset:1152
	ds_write_b16_d16_hi v69, v83 offset:1296
	ds_write_b16 v70, v85 offset:1152
	ds_write_b16_d16_hi v70, v85 offset:1296
	v_add_f32_e32 v77, 0x41200000, v72
	v_add_f32_e32 v78, 0x41300000, v72
	v_mul_f32_e32 v77, v77, v71
	v_mul_f32_e32 v78, v78, v71
	v_fract_f32_e32 v77, v77
	v_fract_f32_e32 v78, v78
	v_sin_f32_e32 v79, v77
	v_sin_f32_e32 v80, v78
	v_cos_f32_e32 v81, v77
	v_cos_f32_e32 v82, v78
	v_mul_f32_e32 v83, v24, v81
	v_mul_f32_e32 v84, v25, v82
	v_mul_f32_e32 v85, v56, v81
	v_mul_f32_e32 v86, v57, v82
	v_fma_f32 v83, -v56, v79, v83
	v_fma_f32 v84, -v57, v80, v84
	v_fmac_f32_e32 v85, v24, v79
	v_fmac_f32_e32 v86, v25, v80
	v_cvt_pk_bf16_f32 v83, v83, v84
	v_cvt_pk_bf16_f32 v85, v85, v86
	ds_write_b16 v69, v83 offset:1440
	ds_write_b16_d16_hi v69, v83 offset:1584
	ds_write_b16 v70, v85 offset:1440
	ds_write_b16_d16_hi v70, v85 offset:1584
	v_add_f32_e32 v77, 0x41800000, v72
	v_add_f32_e32 v78, 0x41880000, v72
	v_mul_f32_e32 v77, v77, v71
	v_mul_f32_e32 v78, v78, v71
	v_fract_f32_e32 v77, v77
	v_fract_f32_e32 v78, v78
	v_sin_f32_e32 v79, v77
	v_sin_f32_e32 v80, v78
	v_cos_f32_e32 v81, v77
	v_cos_f32_e32 v82, v78
	v_mul_f32_e32 v83, v26, v81
	v_mul_f32_e32 v84, v27, v82
	v_mul_f32_e32 v85, v58, v81
	v_mul_f32_e32 v86, v59, v82
	v_fma_f32 v83, -v58, v79, v83
	v_fma_f32 v84, -v59, v80, v84
	v_fmac_f32_e32 v85, v26, v79
	v_fmac_f32_e32 v86, v27, v80
	v_cvt_pk_bf16_f32 v83, v83, v84
	v_cvt_pk_bf16_f32 v85, v85, v86
	ds_write_b16 v69, v83 offset:2304
	ds_write_b16_d16_hi v69, v83 offset:2448
	ds_write_b16 v70, v85 offset:2304
	ds_write_b16_d16_hi v70, v85 offset:2448
	v_add_f32_e32 v77, 0x41900000, v72
	v_add_f32_e32 v78, 0x41980000, v72
	v_mul_f32_e32 v77, v77, v71
	v_mul_f32_e32 v78, v78, v71
	v_fract_f32_e32 v77, v77
	v_fract_f32_e32 v78, v78
	v_sin_f32_e32 v79, v77
	v_sin_f32_e32 v80, v78
	v_cos_f32_e32 v81, v77
	v_cos_f32_e32 v82, v78
	v_mul_f32_e32 v83, v28, v81
	v_mul_f32_e32 v84, v29, v82
	v_mul_f32_e32 v85, v60, v81
	v_mul_f32_e32 v86, v61, v82
	v_fma_f32 v83, -v60, v79, v83
	v_fma_f32 v84, -v61, v80, v84
	v_fmac_f32_e32 v85, v28, v79
	v_fmac_f32_e32 v86, v29, v80
	v_cvt_pk_bf16_f32 v83, v83, v84
	v_cvt_pk_bf16_f32 v85, v85, v86
	ds_write_b16 v69, v83 offset:2592
	ds_write_b16_d16_hi v69, v83 offset:2736
	ds_write_b16 v70, v85 offset:2592
	ds_write_b16_d16_hi v70, v85 offset:2736
	v_add_f32_e32 v77, 0x41c00000, v72
	v_add_f32_e32 v78, 0x41c80000, v72
	v_mul_f32_e32 v77, v77, v71
	v_mul_f32_e32 v78, v78, v71
	v_fract_f32_e32 v77, v77
	v_fract_f32_e32 v78, v78
	v_sin_f32_e32 v79, v77
	v_sin_f32_e32 v80, v78
	v_cos_f32_e32 v81, v77
	v_cos_f32_e32 v82, v78
	v_mul_f32_e32 v83, v30, v81
	v_mul_f32_e32 v84, v31, v82
	v_mul_f32_e32 v85, v62, v81
	v_mul_f32_e32 v86, v63, v82
	v_fma_f32 v83, -v62, v79, v83
	v_fma_f32 v84, -v63, v80, v84
	v_fmac_f32_e32 v85, v30, v79
	v_fmac_f32_e32 v86, v31, v80
	v_cvt_pk_bf16_f32 v83, v83, v84
	v_cvt_pk_bf16_f32 v85, v85, v86
	ds_write_b16 v69, v83 offset:3456
	ds_write_b16_d16_hi v69, v83 offset:3600
	ds_write_b16 v70, v85 offset:3456
	ds_write_b16_d16_hi v70, v85 offset:3600
	v_add_f32_e32 v77, 0x41d00000, v72
	v_add_f32_e32 v78, 0x41d80000, v72
	v_mul_f32_e32 v77, v77, v71
	v_mul_f32_e32 v78, v78, v71
	v_fract_f32_e32 v77, v77
	v_fract_f32_e32 v78, v78
	v_sin_f32_e32 v79, v77
	v_sin_f32_e32 v80, v78
	v_cos_f32_e32 v81, v77
	v_cos_f32_e32 v82, v78
	v_mul_f32_e32 v83, v32, v81
	v_mul_f32_e32 v84, v33, v82
	v_mul_f32_e32 v85, v64, v81
	v_mul_f32_e32 v86, v65, v82
	v_fma_f32 v83, -v64, v79, v83
	v_fma_f32 v84, -v65, v80, v84
	v_fmac_f32_e32 v85, v32, v79
	v_fmac_f32_e32 v86, v33, v80
	v_cvt_pk_bf16_f32 v83, v83, v84
	v_cvt_pk_bf16_f32 v85, v85, v86
	ds_write_b16 v69, v83 offset:3744
	ds_write_b16_d16_hi v69, v83 offset:3888
	ds_write_b16 v70, v85 offset:3744
	ds_write_b16_d16_hi v70, v85 offset:3888
	v_add_f32_e32 v77, 0x42000000, v72
	v_add_f32_e32 v78, 0x42040000, v72
	v_mul_f32_e32 v77, v77, v71
	v_mul_f32_e32 v78, v78, v71
	v_fract_f32_e32 v77, v77
	v_fract_f32_e32 v78, v78
	v_sin_f32_e32 v79, v77
	v_sin_f32_e32 v80, v78
	v_cos_f32_e32 v81, v77
	v_cos_f32_e32 v82, v78
	v_mul_f32_e32 v83, v2, v81
	v_mul_f32_e32 v84, v3, v82
	v_mul_f32_e32 v85, v34, v81
	v_mul_f32_e32 v86, v35, v82
	v_fma_f32 v83, -v34, v79, v83
	v_fma_f32 v84, -v35, v80, v84
	v_fmac_f32_e32 v85, v2, v79
	v_fmac_f32_e32 v86, v3, v80
	v_cvt_pk_bf16_f32 v83, v83, v84
	v_cvt_pk_bf16_f32 v85, v85, v86
	ds_write_b16 v69, v83 offset:4608
	ds_write_b16_d16_hi v69, v83 offset:4752
	ds_write_b16 v70, v85 offset:4608
	ds_write_b16_d16_hi v70, v85 offset:4752
	v_add_f32_e32 v77, 0x42080000, v72
	v_add_f32_e32 v78, 0x420c0000, v72
	v_mul_f32_e32 v77, v77, v71
	v_mul_f32_e32 v78, v78, v71
	v_fract_f32_e32 v77, v77
	v_fract_f32_e32 v78, v78
	v_sin_f32_e32 v79, v77
	v_sin_f32_e32 v80, v78
	v_cos_f32_e32 v81, v77
	v_cos_f32_e32 v82, v78
	v_mul_f32_e32 v83, v4, v81
	v_mul_f32_e32 v84, v5, v82
	v_mul_f32_e32 v85, v36, v81
	v_mul_f32_e32 v86, v37, v82
	v_fma_f32 v83, -v36, v79, v83
	v_fma_f32 v84, -v37, v80, v84
	v_fmac_f32_e32 v85, v4, v79
	v_fmac_f32_e32 v86, v5, v80
	v_cvt_pk_bf16_f32 v83, v83, v84
	v_cvt_pk_bf16_f32 v85, v85, v86
	ds_write_b16 v69, v83 offset:4896
	ds_write_b16_d16_hi v69, v83 offset:5040
	ds_write_b16 v70, v85 offset:4896
	ds_write_b16_d16_hi v70, v85 offset:5040
	v_add_f32_e32 v77, 0x42200000, v72
	v_add_f32_e32 v78, 0x42240000, v72
	v_mul_f32_e32 v77, v77, v71
	v_mul_f32_e32 v78, v78, v71
	v_fract_f32_e32 v77, v77
	v_fract_f32_e32 v78, v78
	v_sin_f32_e32 v79, v77
	v_sin_f32_e32 v80, v78
	v_cos_f32_e32 v81, v77
	v_cos_f32_e32 v82, v78
	v_mul_f32_e32 v83, v6, v81
	v_mul_f32_e32 v84, v7, v82
	v_mul_f32_e32 v85, v38, v81
	v_mul_f32_e32 v86, v39, v82
	v_fma_f32 v83, -v38, v79, v83
	v_fma_f32 v84, -v39, v80, v84
	v_fmac_f32_e32 v85, v6, v79
	v_fmac_f32_e32 v86, v7, v80
	v_cvt_pk_bf16_f32 v83, v83, v84
	v_cvt_pk_bf16_f32 v85, v85, v86
	ds_write_b16 v69, v83 offset:5760
	ds_write_b16_d16_hi v69, v83 offset:5904
	ds_write_b16 v70, v85 offset:5760
	ds_write_b16_d16_hi v70, v85 offset:5904
	v_add_f32_e32 v77, 0x42280000, v72
	v_add_f32_e32 v78, 0x422c0000, v72
	v_mul_f32_e32 v77, v77, v71
	v_mul_f32_e32 v78, v78, v71
	v_fract_f32_e32 v77, v77
	v_fract_f32_e32 v78, v78
	v_sin_f32_e32 v79, v77
	v_sin_f32_e32 v80, v78
	v_cos_f32_e32 v81, v77
	v_cos_f32_e32 v82, v78
	v_mul_f32_e32 v83, v8, v81
	v_mul_f32_e32 v84, v9, v82
	v_mul_f32_e32 v85, v40, v81
	v_mul_f32_e32 v86, v41, v82
	v_fma_f32 v83, -v40, v79, v83
	v_fma_f32 v84, -v41, v80, v84
	v_fmac_f32_e32 v85, v8, v79
	v_fmac_f32_e32 v86, v9, v80
	v_cvt_pk_bf16_f32 v83, v83, v84
	v_cvt_pk_bf16_f32 v85, v85, v86
	ds_write_b16 v69, v83 offset:6048
	ds_write_b16_d16_hi v69, v83 offset:6192
	ds_write_b16 v70, v85 offset:6048
	ds_write_b16_d16_hi v70, v85 offset:6192
	v_add_f32_e32 v77, 0x42400000, v72
	v_add_f32_e32 v78, 0x42440000, v72
	v_mul_f32_e32 v77, v77, v71
	v_mul_f32_e32 v78, v78, v71
	v_fract_f32_e32 v77, v77
	v_fract_f32_e32 v78, v78
	v_sin_f32_e32 v79, v77
	v_sin_f32_e32 v80, v78
	v_cos_f32_e32 v81, v77
	v_cos_f32_e32 v82, v78
	v_mul_f32_e32 v83, v10, v81
	v_mul_f32_e32 v84, v11, v82
	v_mul_f32_e32 v85, v42, v81
	v_mul_f32_e32 v86, v43, v82
	v_fma_f32 v83, -v42, v79, v83
	v_fma_f32 v84, -v43, v80, v84
	v_fmac_f32_e32 v85, v10, v79
	v_fmac_f32_e32 v86, v11, v80
	v_cvt_pk_bf16_f32 v83, v83, v84
	v_cvt_pk_bf16_f32 v85, v85, v86
	ds_write_b16 v69, v83 offset:6912
	ds_write_b16_d16_hi v69, v83 offset:7056
	ds_write_b16 v70, v85 offset:6912
	ds_write_b16_d16_hi v70, v85 offset:7056
	v_add_f32_e32 v77, 0x42480000, v72
	v_add_f32_e32 v78, 0x424c0000, v72
	v_mul_f32_e32 v77, v77, v71
	v_mul_f32_e32 v78, v78, v71
	v_fract_f32_e32 v77, v77
	v_fract_f32_e32 v78, v78
	v_sin_f32_e32 v79, v77
	v_sin_f32_e32 v80, v78
	v_cos_f32_e32 v81, v77
	v_cos_f32_e32 v82, v78
	v_mul_f32_e32 v83, v12, v81
	v_mul_f32_e32 v84, v13, v82
	v_mul_f32_e32 v85, v44, v81
	v_mul_f32_e32 v86, v45, v82
	v_fma_f32 v83, -v44, v79, v83
	v_fma_f32 v84, -v45, v80, v84
	v_fmac_f32_e32 v85, v12, v79
	v_fmac_f32_e32 v86, v13, v80
	v_cvt_pk_bf16_f32 v83, v83, v84
	v_cvt_pk_bf16_f32 v85, v85, v86
	ds_write_b16 v69, v83 offset:7200
	ds_write_b16_d16_hi v69, v83 offset:7344
	ds_write_b16 v70, v85 offset:7200
	ds_write_b16_d16_hi v70, v85 offset:7344
	v_add_f32_e32 v77, 0x42600000, v72
	v_add_f32_e32 v78, 0x42640000, v72
	v_mul_f32_e32 v77, v77, v71
	v_mul_f32_e32 v78, v78, v71
	v_fract_f32_e32 v77, v77
	v_fract_f32_e32 v78, v78
	v_sin_f32_e32 v79, v77
	v_sin_f32_e32 v80, v78
	v_cos_f32_e32 v81, v77
	v_cos_f32_e32 v82, v78
	v_mul_f32_e32 v83, v14, v81
	v_mul_f32_e32 v84, v15, v82
	v_mul_f32_e32 v85, v46, v81
	v_mul_f32_e32 v86, v47, v82
	v_fma_f32 v83, -v46, v79, v83
	v_fma_f32 v84, -v47, v80, v84
	v_fmac_f32_e32 v85, v14, v79
	v_fmac_f32_e32 v86, v15, v80
	v_cvt_pk_bf16_f32 v83, v83, v84
	v_cvt_pk_bf16_f32 v85, v85, v86
	ds_write_b16 v69, v83 offset:8064
	ds_write_b16_d16_hi v69, v83 offset:8208
	ds_write_b16 v70, v85 offset:8064
	ds_write_b16_d16_hi v70, v85 offset:8208
	v_add_f32_e32 v77, 0x42680000, v72
	v_add_f32_e32 v78, 0x426c0000, v72
	v_mul_f32_e32 v77, v77, v71
	v_mul_f32_e32 v78, v78, v71
	v_fract_f32_e32 v77, v77
	v_fract_f32_e32 v78, v78
	v_sin_f32_e32 v79, v77
	v_sin_f32_e32 v80, v78
	v_cos_f32_e32 v81, v77
	v_cos_f32_e32 v82, v78
	v_mul_f32_e32 v83, v16, v81
	v_mul_f32_e32 v84, v17, v82
	v_mul_f32_e32 v85, v48, v81
	v_mul_f32_e32 v86, v49, v82
	v_fma_f32 v83, -v48, v79, v83
	v_fma_f32 v84, -v49, v80, v84
	v_fmac_f32_e32 v85, v16, v79
	v_fmac_f32_e32 v86, v17, v80
	v_cvt_pk_bf16_f32 v83, v83, v84
	v_cvt_pk_bf16_f32 v85, v85, v86
	ds_write_b16 v69, v83 offset:8352
	ds_write_b16_d16_hi v69, v83 offset:8496
	ds_write_b16 v70, v85 offset:8352
	ds_write_b16_d16_hi v70, v85 offset:8496
	s_branch .Lep_rowstore
.Lep_c1_norope:
	s_cmp_eq_u32 s15, 0
	s_cbranch_scc1 .Lep_c1_plain_ns
	v_mul_f32_e32 v77, v18, v76
	v_mul_f32_e32 v79, v19, v76
	v_mul_f32_e32 v78, v50, v76
	v_mul_f32_e32 v80, v51, v76
	v_cvt_pk_bf16_f32 v77, v77, v79
	v_cvt_pk_bf16_f32 v78, v78, v80
	ds_write_b16 v69, v77 offset:0
	ds_write_b16_d16_hi v69, v77 offset:144
	ds_write_b16 v70, v78 offset:0
	ds_write_b16_d16_hi v70, v78 offset:144
	v_mul_f32_e32 v77, v20, v76
	v_mul_f32_e32 v79, v21, v76
	v_mul_f32_e32 v78, v52, v76
	v_mul_f32_e32 v80, v53, v76
	v_cvt_pk_bf16_f32 v77, v77, v79
	v_cvt_pk_bf16_f32 v78, v78, v80
	ds_write_b16 v69, v77 offset:288
	ds_write_b16_d16_hi v69, v77 offset:432
	ds_write_b16 v70, v78 offset:288
	ds_write_b16_d16_hi v70, v78 offset:432
	v_mul_f32_e32 v77, v22, v76
	v_mul_f32_e32 v79, v23, v76
	v_mul_f32_e32 v78, v54, v76
	v_mul_f32_e32 v80, v55, v76
	v_cvt_pk_bf16_f32 v77, v77, v79
	v_cvt_pk_bf16_f32 v78, v78, v80
	ds_write_b16 v69, v77 offset:1152
	ds_write_b16_d16_hi v69, v77 offset:1296
	ds_write_b16 v70, v78 offset:1152
	ds_write_b16_d16_hi v70, v78 offset:1296
	v_mul_f32_e32 v77, v24, v76
	v_mul_f32_e32 v79, v25, v76
	v_mul_f32_e32 v78, v56, v76
	v_mul_f32_e32 v80, v57, v76
	v_cvt_pk_bf16_f32 v77, v77, v79
	v_cvt_pk_bf16_f32 v78, v78, v80
	ds_write_b16 v69, v77 offset:1440
	ds_write_b16_d16_hi v69, v77 offset:1584
	ds_write_b16 v70, v78 offset:1440
	ds_write_b16_d16_hi v70, v78 offset:1584
	v_mul_f32_e32 v77, v26, v76
	v_mul_f32_e32 v79, v27, v76
	v_mul_f32_e32 v78, v58, v76
	v_mul_f32_e32 v80, v59, v76
	v_cvt_pk_bf16_f32 v77, v77, v79
	v_cvt_pk_bf16_f32 v78, v78, v80
	ds_write_b16 v69, v77 offset:2304
	ds_write_b16_d16_hi v69, v77 offset:2448
	ds_write_b16 v70, v78 offset:2304
	ds_write_b16_d16_hi v70, v78 offset:2448
	v_mul_f32_e32 v77, v28, v76
	v_mul_f32_e32 v79, v29, v76
	v_mul_f32_e32 v78, v60, v76
	v_mul_f32_e32 v80, v61, v76
	v_cvt_pk_bf16_f32 v77, v77, v79
	v_cvt_pk_bf16_f32 v78, v78, v80
	ds_write_b16 v69, v77 offset:2592
	ds_write_b16_d16_hi v69, v77 offset:2736
	ds_write_b16 v70, v78 offset:2592
	ds_write_b16_d16_hi v70, v78 offset:2736
	v_mul_f32_e32 v77, v30, v76
	v_mul_f32_e32 v79, v31, v76
	v_mul_f32_e32 v78, v62, v76
	v_mul_f32_e32 v80, v63, v76
	v_cvt_pk_bf16_f32 v77, v77, v79
	v_cvt_pk_bf16_f32 v78, v78, v80
	ds_write_b16 v69, v77 offset:3456
	ds_write_b16_d16_hi v69, v77 offset:3600
	ds_write_b16 v70, v78 offset:3456
	ds_write_b16_d16_hi v70, v78 offset:3600
	v_mul_f32_e32 v77, v32, v76
	v_mul_f32_e32 v79, v33, v76
	v_mul_f32_e32 v78, v64, v76
	v_mul_f32_e32 v80, v65, v76
	v_cvt_pk_bf16_f32 v77, v77, v79
	v_cvt_pk_bf16_f32 v78, v78, v80
	ds_write_b16 v69, v77 offset:3744
	ds_write_b16_d16_hi v69, v77 offset:3888
	ds_write_b16 v70, v78 offset:3744
	ds_write_b16_d16_hi v70, v78 offset:3888
	v_mul_f32_e32 v77, v2, v76
	v_mul_f32_e32 v79, v3, v76
	v_mul_f32_e32 v78, v34, v76
	v_mul_f32_e32 v80, v35, v76
	v_cvt_pk_bf16_f32 v77, v77, v79
	v_cvt_pk_bf16_f32 v78, v78, v80
	ds_write_b16 v69, v77 offset:4608
	ds_write_b16_d16_hi v69, v77 offset:4752
	ds_write_b16 v70, v78 offset:4608
	ds_write_b16_d16_hi v70, v78 offset:4752
	v_mul_f32_e32 v77, v4, v76
	v_mul_f32_e32 v79, v5, v76
	v_mul_f32_e32 v78, v36, v76
	v_mul_f32_e32 v80, v37, v76
	v_cvt_pk_bf16_f32 v77, v77, v79
	v_cvt_pk_bf16_f32 v78, v78, v80
	ds_write_b16 v69, v77 offset:4896
	ds_write_b16_d16_hi v69, v77 offset:5040
	ds_write_b16 v70, v78 offset:4896
	ds_write_b16_d16_hi v70, v78 offset:5040
	v_mul_f32_e32 v77, v6, v76
	v_mul_f32_e32 v79, v7, v76
	v_mul_f32_e32 v78, v38, v76
	v_mul_f32_e32 v80, v39, v76
	v_cvt_pk_bf16_f32 v77, v77, v79
	v_cvt_pk_bf16_f32 v78, v78, v80
	ds_write_b16 v69, v77 offset:5760
	ds_write_b16_d16_hi v69, v77 offset:5904
	ds_write_b16 v70, v78 offset:5760
	ds_write_b16_d16_hi v70, v78 offset:5904
	v_mul_f32_e32 v77, v8, v76
	v_mul_f32_e32 v79, v9, v76
	v_mul_f32_e32 v78, v40, v76
	v_mul_f32_e32 v80, v41, v76
	v_cvt_pk_bf16_f32 v77, v77, v79
	v_cvt_pk_bf16_f32 v78, v78, v80
	ds_write_b16 v69, v77 offset:6048
	ds_write_b16_d16_hi v69, v77 offset:6192
	ds_write_b16 v70, v78 offset:6048
	ds_write_b16_d16_hi v70, v78 offset:6192
	v_mul_f32_e32 v77, v10, v76
	v_mul_f32_e32 v79, v11, v76
	v_mul_f32_e32 v78, v42, v76
	v_mul_f32_e32 v80, v43, v76
	v_cvt_pk_bf16_f32 v77, v77, v79
	v_cvt_pk_bf16_f32 v78, v78, v80
	ds_write_b16 v69, v77 offset:6912
	ds_write_b16_d16_hi v69, v77 offset:7056
	ds_write_b16 v70, v78 offset:6912
	ds_write_b16_d16_hi v70, v78 offset:7056
	v_mul_f32_e32 v77, v12, v76
	v_mul_f32_e32 v79, v13, v76
	v_mul_f32_e32 v78, v44, v76
	v_mul_f32_e32 v80, v45, v76
	v_cvt_pk_bf16_f32 v77, v77, v79
	v_cvt_pk_bf16_f32 v78, v78, v80
	ds_write_b16 v69, v77 offset:7200
	ds_write_b16_d16_hi v69, v77 offset:7344
	ds_write_b16 v70, v78 offset:7200
	ds_write_b16_d16_hi v70, v78 offset:7344
	v_mul_f32_e32 v77, v14, v76
	v_mul_f32_e32 v79, v15, v76
	v_mul_f32_e32 v78, v46, v76
	v_mul_f32_e32 v80, v47, v76
	v_cvt_pk_bf16_f32 v77, v77, v79
	v_cvt_pk_bf16_f32 v78, v78, v80
	ds_write_b16 v69, v77 offset:8064
	ds_write_b16_d16_hi v69, v77 offset:8208
	ds_write_b16 v70, v78 offset:8064
	ds_write_b16_d16_hi v70, v78 offset:8208
	v_mul_f32_e32 v77, v16, v76
	v_mul_f32_e32 v79, v17, v76
	v_mul_f32_e32 v78, v48, v76
	v_mul_f32_e32 v80, v49, v76
	v_cvt_pk_bf16_f32 v77, v77, v79
	v_cvt_pk_bf16_f32 v78, v78, v80
	ds_write_b16 v69, v77 offset:8352
	ds_write_b16_d16_hi v69, v77 offset:8496
	ds_write_b16 v70, v78 offset:8352
	ds_write_b16_d16_hi v70, v78 offset:8496
	s_branch .Lep_rowstore
.Lep_c1_plain_ns:
	v_cvt_pk_bf16_f32 v77, v18, v19
	v_cvt_pk_bf16_f32 v78, v50, v51
	ds_write_b16 v69, v77 offset:0
	ds_write_b16_d16_hi v69, v77 offset:144
	ds_write_b16 v70, v78 offset:0
	ds_write_b16_d16_hi v70, v78 offset:144
	v_cvt_pk_bf16_f32 v77, v20, v21
	v_cvt_pk_bf16_f32 v78, v52, v53
	ds_write_b16 v69, v77 offset:288
	ds_write_b16_d16_hi v69, v77 offset:432
	ds_write_b16 v70, v78 offset:288
	ds_write_b16_d16_hi v70, v78 offset:432
	v_cvt_pk_bf16_f32 v77, v22, v23
	v_cvt_pk_bf16_f32 v78, v54, v55
	ds_write_b16 v69, v77 offset:1152
	ds_write_b16_d16_hi v69, v77 offset:1296
	ds_write_b16 v70, v78 offset:1152
	ds_write_b16_d16_hi v70, v78 offset:1296
	v_cvt_pk_bf16_f32 v77, v24, v25
	v_cvt_pk_bf16_f32 v78, v56, v57
	ds_write_b16 v69, v77 offset:1440
	ds_write_b16_d16_hi v69, v77 offset:1584
	ds_write_b16 v70, v78 offset:1440
	ds_write_b16_d16_hi v70, v78 offset:1584
	v_cvt_pk_bf16_f32 v77, v26, v27
	v_cvt_pk_bf16_f32 v78, v58, v59
	ds_write_b16 v69, v77 offset:2304
	ds_write_b16_d16_hi v69, v77 offset:2448
	ds_write_b16 v70, v78 offset:2304
	ds_write_b16_d16_hi v70, v78 offset:2448
	v_cvt_pk_bf16_f32 v77, v28, v29
	v_cvt_pk_bf16_f32 v78, v60, v61
	ds_write_b16 v69, v77 offset:2592
	ds_write_b16_d16_hi v69, v77 offset:2736
	ds_write_b16 v70, v78 offset:2592
	ds_write_b16_d16_hi v70, v78 offset:2736
	v_cvt_pk_bf16_f32 v77, v30, v31
	v_cvt_pk_bf16_f32 v78, v62, v63
	ds_write_b16 v69, v77 offset:3456
	ds_write_b16_d16_hi v69, v77 offset:3600
	ds_write_b16 v70, v78 offset:3456
	ds_write_b16_d16_hi v70, v78 offset:3600
	v_cvt_pk_bf16_f32 v77, v32, v33
	v_cvt_pk_bf16_f32 v78, v64, v65
	ds_write_b16 v69, v77 offset:3744
	ds_write_b16_d16_hi v69, v77 offset:3888
	ds_write_b16 v70, v78 offset:3744
	ds_write_b16_d16_hi v70, v78 offset:3888
	v_cvt_pk_bf16_f32 v77, v2, v3
	v_cvt_pk_bf16_f32 v78, v34, v35
	ds_write_b16 v69, v77 offset:4608
	ds_write_b16_d16_hi v69, v77 offset:4752
	ds_write_b16 v70, v78 offset:4608
	ds_write_b16_d16_hi v70, v78 offset:4752
	v_cvt_pk_bf16_f32 v77, v4, v5
	v_cvt_pk_bf16_f32 v78, v36, v37
	ds_write_b16 v69, v77 offset:4896
	ds_write_b16_d16_hi v69, v77 offset:5040
	ds_write_b16 v70, v78 offset:4896
	ds_write_b16_d16_hi v70, v78 offset:5040
	v_cvt_pk_bf16_f32 v77, v6, v7
	v_cvt_pk_bf16_f32 v78, v38, v39
	ds_write_b16 v69, v77 offset:5760
	ds_write_b16_d16_hi v69, v77 offset:5904
	ds_write_b16 v70, v78 offset:5760
	ds_write_b16_d16_hi v70, v78 offset:5904
	v_cvt_pk_bf16_f32 v77, v8, v9
	v_cvt_pk_bf16_f32 v78, v40, v41
	ds_write_b16 v69, v77 offset:6048
	ds_write_b16_d16_hi v69, v77 offset:6192
	ds_write_b16 v70, v78 offset:6048
	ds_write_b16_d16_hi v70, v78 offset:6192
	v_cvt_pk_bf16_f32 v77, v10, v11
	v_cvt_pk_bf16_f32 v78, v42, v43
	ds_write_b16 v69, v77 offset:6912
	ds_write_b16_d16_hi v69, v77 offset:7056
	ds_write_b16 v70, v78 offset:6912
	ds_write_b16_d16_hi v70, v78 offset:7056
	v_cvt_pk_bf16_f32 v77, v12, v13
	v_cvt_pk_bf16_f32 v78, v44, v45
	ds_write_b16 v69, v77 offset:7200
	ds_write_b16_d16_hi v69, v77 offset:7344
	ds_write_b16 v70, v78 offset:7200
	ds_write_b16_d16_hi v70, v78 offset:7344
	v_cvt_pk_bf16_f32 v77, v14, v15
	v_cvt_pk_bf16_f32 v78, v46, v47
	ds_write_b16 v69, v77 offset:8064
	ds_write_b16_d16_hi v69, v77 offset:8208
	ds_write_b16 v70, v78 offset:8064
	ds_write_b16_d16_hi v70, v78 offset:8208
	v_cvt_pk_bf16_f32 v77, v16, v17
	v_cvt_pk_bf16_f32 v78, v48, v49
	ds_write_b16 v69, v77 offset:8352
	ds_write_b16_d16_hi v69, v77 offset:8496
	ds_write_b16 v70, v78 offset:8352
	ds_write_b16_d16_hi v70, v78 offset:8496
	s_branch .Lep_rowstore
.Lep_cat3:
	s_lshl_b32 s16, s16, 6
	s_add_u32 s10, s10, s16
	s_lshl_b32 s73, s0, 7
	s_lshl_b32 s27, s8, 6
	s_add_u32 s73, s73, s27
	s_lshl_b32 s73, s73, 10
	s_add_u32 s73, s73, s10
	s_lshl_b32 s73, s73, 1
	s_add_u32 s10, s80, 0x3a00000
	s_addc_u32 s11, s81, 0
	s_add_u32 s10, s10, s73
	s_addc_u32 s11, s11, 0
	v_lshrrev_b32_e32 v77, 3, v66
	v_and_b32_e32 v78, 7, v66
	v_lshlrev_b32_e32 v75, 11, v77
	v_lshl_add_u32 v75, v78, 4, v75
	v_mul_u32_u24_e32 v69, 0x240, v68
	v_add_u32_e32 v69, s72, v69
	v_lshl_add_u32 v69, v67, 1, v69
	v_add_u32_e32 v70, 64, v69
	v_mul_f32_e32 v77, 0xbfb8aa3b, v18
	v_mul_f32_e32 v78, 0xbfb8aa3b, v19
	v_mul_f32_e32 v79, 0xbfb8aa3b, v50
	v_mul_f32_e32 v80, 0xbfb8aa3b, v51
	v_exp_f32_e32 v77, v77
	v_exp_f32_e32 v78, v78
	v_exp_f32_e32 v79, v79
	v_exp_f32_e32 v80, v80
	v_add_f32_e32 v77, 1.0, v77
	v_add_f32_e32 v78, 1.0, v78
	v_add_f32_e32 v79, 1.0, v79
	v_add_f32_e32 v80, 1.0, v80
	v_rcp_f32_e32 v77, v77
	v_rcp_f32_e32 v78, v78
	v_rcp_f32_e32 v79, v79
	v_rcp_f32_e32 v80, v80
	v_mul_f32_e32 v77, v18, v77
	v_mul_f32_e32 v78, v19, v78
	v_mul_f32_e32 v79, v50, v79
	v_mul_f32_e32 v80, v51, v80
	v_cvt_pk_bf16_f32 v77, v77, v78
	v_cvt_pk_bf16_f32 v79, v79, v80
	ds_write_b16 v69, v77 offset:0
	ds_write_b16_d16_hi v69, v77 offset:144
	ds_write_b16 v70, v79 offset:0
	ds_write_b16_d16_hi v70, v79 offset:144
	v_mul_f32_e32 v77, 0xbfb8aa3b, v20
	v_mul_f32_e32 v78, 0xbfb8aa3b, v21
	v_mul_f32_e32 v79, 0xbfb8aa3b, v52
	v_mul_f32_e32 v80, 0xbfb8aa3b, v53
	v_exp_f32_e32 v77, v77
	v_exp_f32_e32 v78, v78
	v_exp_f32_e32 v79, v79
	v_exp_f32_e32 v80, v80
	v_add_f32_e32 v77, 1.0, v77
	v_add_f32_e32 v78, 1.0, v78
	v_add_f32_e32 v79, 1.0, v79
	v_add_f32_e32 v80, 1.0, v80
	v_rcp_f32_e32 v77, v77
	v_rcp_f32_e32 v78, v78
	v_rcp_f32_e32 v79, v79
	v_rcp_f32_e32 v80, v80
	v_mul_f32_e32 v77, v20, v77
	v_mul_f32_e32 v78, v21, v78
	v_mul_f32_e32 v79, v52, v79
	v_mul_f32_e32 v80, v53, v80
	v_cvt_pk_bf16_f32 v77, v77, v78
	v_cvt_pk_bf16_f32 v79, v79, v80
	ds_write_b16 v69, v77 offset:288
	ds_write_b16_d16_hi v69, v77 offset:432
	ds_write_b16 v70, v79 offset:288
	ds_write_b16_d16_hi v70, v79 offset:432
	v_mul_f32_e32 v77, 0xbfb8aa3b, v22
	v_mul_f32_e32 v78, 0xbfb8aa3b, v23
	v_mul_f32_e32 v79, 0xbfb8aa3b, v54
	v_mul_f32_e32 v80, 0xbfb8aa3b, v55
	v_exp_f32_e32 v77, v77
	v_exp_f32_e32 v78, v78
	v_exp_f32_e32 v79, v79
	v_exp_f32_e32 v80, v80
	v_add_f32_e32 v77, 1.0, v77
	v_add_f32_e32 v78, 1.0, v78
	v_add_f32_e32 v79, 1.0, v79
	v_add_f32_e32 v80, 1.0, v80
	v_rcp_f32_e32 v77, v77
	v_rcp_f32_e32 v78, v78
	v_rcp_f32_e32 v79, v79
	v_rcp_f32_e32 v80, v80
	v_mul_f32_e32 v77, v22, v77
	v_mul_f32_e32 v78, v23, v78
	v_mul_f32_e32 v79, v54, v79
	v_mul_f32_e32 v80, v55, v80
	v_cvt_pk_bf16_f32 v77, v77, v78
	v_cvt_pk_bf16_f32 v79, v79, v80
	ds_write_b16 v69, v77 offset:1152
	ds_write_b16_d16_hi v69, v77 offset:1296
	ds_write_b16 v70, v79 offset:1152
	ds_write_b16_d16_hi v70, v79 offset:1296
	v_mul_f32_e32 v77, 0xbfb8aa3b, v24
	v_mul_f32_e32 v78, 0xbfb8aa3b, v25
	v_mul_f32_e32 v79, 0xbfb8aa3b, v56
	v_mul_f32_e32 v80, 0xbfb8aa3b, v57
	v_exp_f32_e32 v77, v77
	v_exp_f32_e32 v78, v78
	v_exp_f32_e32 v79, v79
	v_exp_f32_e32 v80, v80
	v_add_f32_e32 v77, 1.0, v77
	v_add_f32_e32 v78, 1.0, v78
	v_add_f32_e32 v79, 1.0, v79
	v_add_f32_e32 v80, 1.0, v80
	v_rcp_f32_e32 v77, v77
	v_rcp_f32_e32 v78, v78
	v_rcp_f32_e32 v79, v79
	v_rcp_f32_e32 v80, v80
	v_mul_f32_e32 v77, v24, v77
	v_mul_f32_e32 v78, v25, v78
	v_mul_f32_e32 v79, v56, v79
	v_mul_f32_e32 v80, v57, v80
	v_cvt_pk_bf16_f32 v77, v77, v78
	v_cvt_pk_bf16_f32 v79, v79, v80
	ds_write_b16 v69, v77 offset:1440
	ds_write_b16_d16_hi v69, v77 offset:1584
	ds_write_b16 v70, v79 offset:1440
	ds_write_b16_d16_hi v70, v79 offset:1584
	v_mul_f32_e32 v77, 0xbfb8aa3b, v26
	v_mul_f32_e32 v78, 0xbfb8aa3b, v27
	v_mul_f32_e32 v79, 0xbfb8aa3b, v58
	v_mul_f32_e32 v80, 0xbfb8aa3b, v59
	v_exp_f32_e32 v77, v77
	v_exp_f32_e32 v78, v78
	v_exp_f32_e32 v79, v79
	v_exp_f32_e32 v80, v80
	v_add_f32_e32 v77, 1.0, v77
	v_add_f32_e32 v78, 1.0, v78
	v_add_f32_e32 v79, 1.0, v79
	v_add_f32_e32 v80, 1.0, v80
	v_rcp_f32_e32 v77, v77
	v_rcp_f32_e32 v78, v78
	v_rcp_f32_e32 v79, v79
	v_rcp_f32_e32 v80, v80
	v_mul_f32_e32 v77, v26, v77
	v_mul_f32_e32 v78, v27, v78
	v_mul_f32_e32 v79, v58, v79
	v_mul_f32_e32 v80, v59, v80
	v_cvt_pk_bf16_f32 v77, v77, v78
	v_cvt_pk_bf16_f32 v79, v79, v80
	ds_write_b16 v69, v77 offset:2304
	ds_write_b16_d16_hi v69, v77 offset:2448
	ds_write_b16 v70, v79 offset:2304
	ds_write_b16_d16_hi v70, v79 offset:2448
	v_mul_f32_e32 v77, 0xbfb8aa3b, v28
	v_mul_f32_e32 v78, 0xbfb8aa3b, v29
	v_mul_f32_e32 v79, 0xbfb8aa3b, v60
	v_mul_f32_e32 v80, 0xbfb8aa3b, v61
	v_exp_f32_e32 v77, v77
	v_exp_f32_e32 v78, v78
	v_exp_f32_e32 v79, v79
	v_exp_f32_e32 v80, v80
	v_add_f32_e32 v77, 1.0, v77
	v_add_f32_e32 v78, 1.0, v78
	v_add_f32_e32 v79, 1.0, v79
	v_add_f32_e32 v80, 1.0, v80
	v_rcp_f32_e32 v77, v77
	v_rcp_f32_e32 v78, v78
	v_rcp_f32_e32 v79, v79
	v_rcp_f32_e32 v80, v80
	v_mul_f32_e32 v77, v28, v77
	v_mul_f32_e32 v78, v29, v78
	v_mul_f32_e32 v79, v60, v79
	v_mul_f32_e32 v80, v61, v80
	v_cvt_pk_bf16_f32 v77, v77, v78
	v_cvt_pk_bf16_f32 v79, v79, v80
	ds_write_b16 v69, v77 offset:2592
	ds_write_b16_d16_hi v69, v77 offset:2736
	ds_write_b16 v70, v79 offset:2592
	ds_write_b16_d16_hi v70, v79 offset:2736
	v_mul_f32_e32 v77, 0xbfb8aa3b, v30
	v_mul_f32_e32 v78, 0xbfb8aa3b, v31
	v_mul_f32_e32 v79, 0xbfb8aa3b, v62
	v_mul_f32_e32 v80, 0xbfb8aa3b, v63
	v_exp_f32_e32 v77, v77
	v_exp_f32_e32 v78, v78
	v_exp_f32_e32 v79, v79
	v_exp_f32_e32 v80, v80
	v_add_f32_e32 v77, 1.0, v77
	v_add_f32_e32 v78, 1.0, v78
	v_add_f32_e32 v79, 1.0, v79
	v_add_f32_e32 v80, 1.0, v80
	v_rcp_f32_e32 v77, v77
	v_rcp_f32_e32 v78, v78
	v_rcp_f32_e32 v79, v79
	v_rcp_f32_e32 v80, v80
	v_mul_f32_e32 v77, v30, v77
	v_mul_f32_e32 v78, v31, v78
	v_mul_f32_e32 v79, v62, v79
	v_mul_f32_e32 v80, v63, v80
	v_cvt_pk_bf16_f32 v77, v77, v78
	v_cvt_pk_bf16_f32 v79, v79, v80
	ds_write_b16 v69, v77 offset:3456
	ds_write_b16_d16_hi v69, v77 offset:3600
	ds_write_b16 v70, v79 offset:3456
	ds_write_b16_d16_hi v70, v79 offset:3600
	v_mul_f32_e32 v77, 0xbfb8aa3b, v32
	v_mul_f32_e32 v78, 0xbfb8aa3b, v33
	v_mul_f32_e32 v79, 0xbfb8aa3b, v64
	v_mul_f32_e32 v80, 0xbfb8aa3b, v65
	v_exp_f32_e32 v77, v77
	v_exp_f32_e32 v78, v78
	v_exp_f32_e32 v79, v79
	v_exp_f32_e32 v80, v80
	v_add_f32_e32 v77, 1.0, v77
	v_add_f32_e32 v78, 1.0, v78
	v_add_f32_e32 v79, 1.0, v79
	v_add_f32_e32 v80, 1.0, v80
	v_rcp_f32_e32 v77, v77
	v_rcp_f32_e32 v78, v78
	v_rcp_f32_e32 v79, v79
	v_rcp_f32_e32 v80, v80
	v_mul_f32_e32 v77, v32, v77
	v_mul_f32_e32 v78, v33, v78
	v_mul_f32_e32 v79, v64, v79
	v_mul_f32_e32 v80, v65, v80
	v_cvt_pk_bf16_f32 v77, v77, v78
	v_cvt_pk_bf16_f32 v79, v79, v80
	ds_write_b16 v69, v77 offset:3744
	ds_write_b16_d16_hi v69, v77 offset:3888
	ds_write_b16 v70, v79 offset:3744
	ds_write_b16_d16_hi v70, v79 offset:3888
	v_mul_f32_e32 v77, 0xbfb8aa3b, v2
	v_mul_f32_e32 v78, 0xbfb8aa3b, v3
	v_mul_f32_e32 v79, 0xbfb8aa3b, v34
	v_mul_f32_e32 v80, 0xbfb8aa3b, v35
	v_exp_f32_e32 v77, v77
	v_exp_f32_e32 v78, v78
	v_exp_f32_e32 v79, v79
	v_exp_f32_e32 v80, v80
	v_add_f32_e32 v77, 1.0, v77
	v_add_f32_e32 v78, 1.0, v78
	v_add_f32_e32 v79, 1.0, v79
	v_add_f32_e32 v80, 1.0, v80
	v_rcp_f32_e32 v77, v77
	v_rcp_f32_e32 v78, v78
	v_rcp_f32_e32 v79, v79
	v_rcp_f32_e32 v80, v80
	v_mul_f32_e32 v77, v2, v77
	v_mul_f32_e32 v78, v3, v78
	v_mul_f32_e32 v79, v34, v79
	v_mul_f32_e32 v80, v35, v80
	v_cvt_pk_bf16_f32 v77, v77, v78
	v_cvt_pk_bf16_f32 v79, v79, v80
	ds_write_b16 v69, v77 offset:4608
	ds_write_b16_d16_hi v69, v77 offset:4752
	ds_write_b16 v70, v79 offset:4608
	ds_write_b16_d16_hi v70, v79 offset:4752
	v_mul_f32_e32 v77, 0xbfb8aa3b, v4
	v_mul_f32_e32 v78, 0xbfb8aa3b, v5
	v_mul_f32_e32 v79, 0xbfb8aa3b, v36
	v_mul_f32_e32 v80, 0xbfb8aa3b, v37
	v_exp_f32_e32 v77, v77
	v_exp_f32_e32 v78, v78
	v_exp_f32_e32 v79, v79
	v_exp_f32_e32 v80, v80
	v_add_f32_e32 v77, 1.0, v77
	v_add_f32_e32 v78, 1.0, v78
	v_add_f32_e32 v79, 1.0, v79
	v_add_f32_e32 v80, 1.0, v80
	v_rcp_f32_e32 v77, v77
	v_rcp_f32_e32 v78, v78
	v_rcp_f32_e32 v79, v79
	v_rcp_f32_e32 v80, v80
	v_mul_f32_e32 v77, v4, v77
	v_mul_f32_e32 v78, v5, v78
	v_mul_f32_e32 v79, v36, v79
	v_mul_f32_e32 v80, v37, v80
	v_cvt_pk_bf16_f32 v77, v77, v78
	v_cvt_pk_bf16_f32 v79, v79, v80
	ds_write_b16 v69, v77 offset:4896
	ds_write_b16_d16_hi v69, v77 offset:5040
	ds_write_b16 v70, v79 offset:4896
	ds_write_b16_d16_hi v70, v79 offset:5040
	v_mul_f32_e32 v77, 0xbfb8aa3b, v6
	v_mul_f32_e32 v78, 0xbfb8aa3b, v7
	v_mul_f32_e32 v79, 0xbfb8aa3b, v38
	v_mul_f32_e32 v80, 0xbfb8aa3b, v39
	v_exp_f32_e32 v77, v77
	v_exp_f32_e32 v78, v78
	v_exp_f32_e32 v79, v79
	v_exp_f32_e32 v80, v80
	v_add_f32_e32 v77, 1.0, v77
	v_add_f32_e32 v78, 1.0, v78
	v_add_f32_e32 v79, 1.0, v79
	v_add_f32_e32 v80, 1.0, v80
	v_rcp_f32_e32 v77, v77
	v_rcp_f32_e32 v78, v78
	v_rcp_f32_e32 v79, v79
	v_rcp_f32_e32 v80, v80
	v_mul_f32_e32 v77, v6, v77
	v_mul_f32_e32 v78, v7, v78
	v_mul_f32_e32 v79, v38, v79
	v_mul_f32_e32 v80, v39, v80
	v_cvt_pk_bf16_f32 v77, v77, v78
	v_cvt_pk_bf16_f32 v79, v79, v80
	ds_write_b16 v69, v77 offset:5760
	ds_write_b16_d16_hi v69, v77 offset:5904
	ds_write_b16 v70, v79 offset:5760
	ds_write_b16_d16_hi v70, v79 offset:5904
	v_mul_f32_e32 v77, 0xbfb8aa3b, v8
	v_mul_f32_e32 v78, 0xbfb8aa3b, v9
	v_mul_f32_e32 v79, 0xbfb8aa3b, v40
	v_mul_f32_e32 v80, 0xbfb8aa3b, v41
	v_exp_f32_e32 v77, v77
	v_exp_f32_e32 v78, v78
	v_exp_f32_e32 v79, v79
	v_exp_f32_e32 v80, v80
	v_add_f32_e32 v77, 1.0, v77
	v_add_f32_e32 v78, 1.0, v78
	v_add_f32_e32 v79, 1.0, v79
	v_add_f32_e32 v80, 1.0, v80
	v_rcp_f32_e32 v77, v77
	v_rcp_f32_e32 v78, v78
	v_rcp_f32_e32 v79, v79
	v_rcp_f32_e32 v80, v80
	v_mul_f32_e32 v77, v8, v77
	v_mul_f32_e32 v78, v9, v78
	v_mul_f32_e32 v79, v40, v79
	v_mul_f32_e32 v80, v41, v80
	v_cvt_pk_bf16_f32 v77, v77, v78
	v_cvt_pk_bf16_f32 v79, v79, v80
	ds_write_b16 v69, v77 offset:6048
	ds_write_b16_d16_hi v69, v77 offset:6192
	ds_write_b16 v70, v79 offset:6048
	ds_write_b16_d16_hi v70, v79 offset:6192
	v_mul_f32_e32 v77, 0xbfb8aa3b, v10
	v_mul_f32_e32 v78, 0xbfb8aa3b, v11
	v_mul_f32_e32 v79, 0xbfb8aa3b, v42
	v_mul_f32_e32 v80, 0xbfb8aa3b, v43
	v_exp_f32_e32 v77, v77
	v_exp_f32_e32 v78, v78
	v_exp_f32_e32 v79, v79
	v_exp_f32_e32 v80, v80
	v_add_f32_e32 v77, 1.0, v77
	v_add_f32_e32 v78, 1.0, v78
	v_add_f32_e32 v79, 1.0, v79
	v_add_f32_e32 v80, 1.0, v80
	v_rcp_f32_e32 v77, v77
	v_rcp_f32_e32 v78, v78
	v_rcp_f32_e32 v79, v79
	v_rcp_f32_e32 v80, v80
	v_mul_f32_e32 v77, v10, v77
	v_mul_f32_e32 v78, v11, v78
	v_mul_f32_e32 v79, v42, v79
	v_mul_f32_e32 v80, v43, v80
	v_cvt_pk_bf16_f32 v77, v77, v78
	v_cvt_pk_bf16_f32 v79, v79, v80
	ds_write_b16 v69, v77 offset:6912
	ds_write_b16_d16_hi v69, v77 offset:7056
	ds_write_b16 v70, v79 offset:6912
	ds_write_b16_d16_hi v70, v79 offset:7056
	v_mul_f32_e32 v77, 0xbfb8aa3b, v12
	v_mul_f32_e32 v78, 0xbfb8aa3b, v13
	v_mul_f32_e32 v79, 0xbfb8aa3b, v44
	v_mul_f32_e32 v80, 0xbfb8aa3b, v45
	v_exp_f32_e32 v77, v77
	v_exp_f32_e32 v78, v78
	v_exp_f32_e32 v79, v79
	v_exp_f32_e32 v80, v80
	v_add_f32_e32 v77, 1.0, v77
	v_add_f32_e32 v78, 1.0, v78
	v_add_f32_e32 v79, 1.0, v79
	v_add_f32_e32 v80, 1.0, v80
	v_rcp_f32_e32 v77, v77
	v_rcp_f32_e32 v78, v78
	v_rcp_f32_e32 v79, v79
	v_rcp_f32_e32 v80, v80
	v_mul_f32_e32 v77, v12, v77
	v_mul_f32_e32 v78, v13, v78
	v_mul_f32_e32 v79, v44, v79
	v_mul_f32_e32 v80, v45, v80
	v_cvt_pk_bf16_f32 v77, v77, v78
	v_cvt_pk_bf16_f32 v79, v79, v80
	ds_write_b16 v69, v77 offset:7200
	ds_write_b16_d16_hi v69, v77 offset:7344
	ds_write_b16 v70, v79 offset:7200
	ds_write_b16_d16_hi v70, v79 offset:7344
	v_mul_f32_e32 v77, 0xbfb8aa3b, v14
	v_mul_f32_e32 v78, 0xbfb8aa3b, v15
	v_mul_f32_e32 v79, 0xbfb8aa3b, v46
	v_mul_f32_e32 v80, 0xbfb8aa3b, v47
	v_exp_f32_e32 v77, v77
	v_exp_f32_e32 v78, v78
	v_exp_f32_e32 v79, v79
	v_exp_f32_e32 v80, v80
	v_add_f32_e32 v77, 1.0, v77
	v_add_f32_e32 v78, 1.0, v78
	v_add_f32_e32 v79, 1.0, v79
	v_add_f32_e32 v80, 1.0, v80
	v_rcp_f32_e32 v77, v77
	v_rcp_f32_e32 v78, v78
	v_rcp_f32_e32 v79, v79
	v_rcp_f32_e32 v80, v80
	v_mul_f32_e32 v77, v14, v77
	v_mul_f32_e32 v78, v15, v78
	v_mul_f32_e32 v79, v46, v79
	v_mul_f32_e32 v80, v47, v80
	v_cvt_pk_bf16_f32 v77, v77, v78
	v_cvt_pk_bf16_f32 v79, v79, v80
	ds_write_b16 v69, v77 offset:8064
	ds_write_b16_d16_hi v69, v77 offset:8208
	ds_write_b16 v70, v79 offset:8064
	ds_write_b16_d16_hi v70, v79 offset:8208
	v_mul_f32_e32 v77, 0xbfb8aa3b, v16
	v_mul_f32_e32 v78, 0xbfb8aa3b, v17
	v_mul_f32_e32 v79, 0xbfb8aa3b, v48
	v_mul_f32_e32 v80, 0xbfb8aa3b, v49
	v_exp_f32_e32 v77, v77
	v_exp_f32_e32 v78, v78
	v_exp_f32_e32 v79, v79
	v_exp_f32_e32 v80, v80
	v_add_f32_e32 v77, 1.0, v77
	v_add_f32_e32 v78, 1.0, v78
	v_add_f32_e32 v79, 1.0, v79
	v_add_f32_e32 v80, 1.0, v80
	v_rcp_f32_e32 v77, v77
	v_rcp_f32_e32 v78, v78
	v_rcp_f32_e32 v79, v79
	v_rcp_f32_e32 v80, v80
	v_mul_f32_e32 v77, v16, v77
	v_mul_f32_e32 v78, v17, v78
	v_mul_f32_e32 v79, v48, v79
	v_mul_f32_e32 v80, v49, v80
	v_cvt_pk_bf16_f32 v77, v77, v78
	v_cvt_pk_bf16_f32 v79, v79, v80
	ds_write_b16 v69, v77 offset:8352
	ds_write_b16_d16_hi v69, v77 offset:8496
	ds_write_b16 v70, v79 offset:8352
	ds_write_b16_d16_hi v70, v79 offset:8496
	s_mov_b32 s16, 0x4000
	s_branch .Lep_store_strided
.Lep_cat2:
	s_add_u32 s10, s10, s17
	s_lshl_b32 s73, s10, 20
	s_lshr_b32 s84, s10, 12
	s_add_u32 s10, s80, s73
	s_addc_u32 s11, s81, s84
	s_lshl_b32 s73, s26, 1
	s_add_u32 s10, s10, s73
	s_addc_u32 s11, s11, 0
	v_lshrrev_b32_e32 v77, 3, v66
	v_and_b32_e32 v78, 7, v66
	v_lshlrev_b32_e32 v75, 14, v77
	v_lshl_add_u32 v75, v78, 4, v75
	v_mul_u32_u24_e32 v69, 0x90, v67
	v_lshl_add_u32 v69, v68, 3, v69
	v_add_u32_e32 v69, s72, v69
	v_cvt_pk_bf16_f32 v78, v18, v19
	v_cvt_pk_bf16_f32 v79, v20, v21
	ds_write_b64 v69, v[78:79] offset:0
	v_cvt_pk_bf16_f32 v80, v22, v23
	v_cvt_pk_bf16_f32 v81, v24, v25
	ds_write_b64 v69, v[80:81] offset:16
	v_cvt_pk_bf16_f32 v82, v26, v27
	v_cvt_pk_bf16_f32 v83, v28, v29
	ds_write_b64 v69, v[82:83] offset:32
	v_cvt_pk_bf16_f32 v84, v30, v31
	v_cvt_pk_bf16_f32 v85, v32, v33
	ds_write_b64 v69, v[84:85] offset:48
	v_cvt_pk_bf16_f32 v78, v50, v51
	v_cvt_pk_bf16_f32 v79, v52, v53
	ds_write_b64 v69, v[78:79] offset:4608
	v_cvt_pk_bf16_f32 v80, v54, v55
	v_cvt_pk_bf16_f32 v81, v56, v57
	ds_write_b64 v69, v[80:81] offset:4624
	v_cvt_pk_bf16_f32 v82, v58, v59
	v_cvt_pk_bf16_f32 v83, v60, v61
	ds_write_b64 v69, v[82:83] offset:4640
	v_cvt_pk_bf16_f32 v84, v62, v63
	v_cvt_pk_bf16_f32 v85, v64, v65
	ds_write_b64 v69, v[84:85] offset:4656
	v_cvt_pk_bf16_f32 v78, v2, v3
	v_cvt_pk_bf16_f32 v79, v4, v5
	ds_write_b64 v69, v[78:79] offset:64
	v_cvt_pk_bf16_f32 v80, v6, v7
	v_cvt_pk_bf16_f32 v81, v8, v9
	ds_write_b64 v69, v[80:81] offset:80
	v_cvt_pk_bf16_f32 v82, v10, v11
	v_cvt_pk_bf16_f32 v83, v12, v13
	ds_write_b64 v69, v[82:83] offset:96
	v_cvt_pk_bf16_f32 v84, v14, v15
	v_cvt_pk_bf16_f32 v85, v16, v17
	ds_write_b64 v69, v[84:85] offset:112
	v_cvt_pk_bf16_f32 v78, v34, v35
	v_cvt_pk_bf16_f32 v79, v36, v37
	ds_write_b64 v69, v[78:79] offset:4672
	v_cvt_pk_bf16_f32 v80, v38, v39
	v_cvt_pk_bf16_f32 v81, v40, v41
	ds_write_b64 v69, v[80:81] offset:4688
	v_cvt_pk_bf16_f32 v82, v42, v43
	v_cvt_pk_bf16_f32 v83, v44, v45
	ds_write_b64 v69, v[82:83] offset:4704
	v_cvt_pk_bf16_f32 v84, v46, v47
	v_cvt_pk_bf16_f32 v85, v48, v49
	ds_write_b64 v69, v[84:85] offset:4720
	s_mov_b32 s16, 0x20000
	s_branch .Lep_store_strided
.Lep_rowstore:
	ds_read_b128 v[180:183], v74 offset:0
	ds_read_b128 v[184:187], v74 offset:1152
	ds_read_b128 v[188:191], v74 offset:2304
	ds_read_b128 v[192:195], v74 offset:3456
	ds_read_b128 v[212:215], v74 offset:4608
	ds_read_b128 v[216:219], v74 offset:5760
	ds_read_b128 v[220:223], v74 offset:6912
	ds_read_b128 v[224:227], v74 offset:8064
	s_waitcnt lgkmcnt(7)
	global_store_dwordx4 v75, v[180:183], s[10:11] offset:0
	s_waitcnt lgkmcnt(6)
	global_store_dwordx4 v75, v[184:187], s[10:11] offset:1024
	s_waitcnt lgkmcnt(5)
	global_store_dwordx4 v75, v[188:191], s[10:11] offset:2048
	s_waitcnt lgkmcnt(4)
	global_store_dwordx4 v75, v[192:195], s[10:11] offset:3072
	s_add_u32 s10, s10, 0x1000
	s_addc_u32 s11, s11, 0
	s_waitcnt lgkmcnt(3)
	global_store_dwordx4 v75, v[212:215], s[10:11] offset:0
	s_waitcnt lgkmcnt(2)
	global_store_dwordx4 v75, v[216:219], s[10:11] offset:1024
	s_waitcnt lgkmcnt(1)
	global_store_dwordx4 v75, v[220:223], s[10:11] offset:2048
	s_waitcnt lgkmcnt(0)
	global_store_dwordx4 v75, v[224:227], s[10:11] offset:3072
	s_branch .LBB0_173
.Lep_store_strided:
	ds_read_b128 v[180:183], v74 offset:0
	ds_read_b128 v[184:187], v74 offset:1152
	ds_read_b128 v[188:191], v74 offset:2304
	ds_read_b128 v[192:195], v74 offset:3456
	ds_read_b128 v[212:215], v74 offset:4608
	ds_read_b128 v[216:219], v74 offset:5760
	ds_read_b128 v[220:223], v74 offset:6912
	ds_read_b128 v[224:227], v74 offset:8064
	s_waitcnt lgkmcnt(7)
	global_store_dwordx4 v75, v[180:183], s[10:11]
	s_add_u32 s10, s10, s16
	s_addc_u32 s11, s11, 0
	s_waitcnt lgkmcnt(6)
	global_store_dwordx4 v75, v[184:187], s[10:11]
	s_add_u32 s10, s10, s16
	s_addc_u32 s11, s11, 0
	s_waitcnt lgkmcnt(5)
	global_store_dwordx4 v75, v[188:191], s[10:11]
	s_add_u32 s10, s10, s16
	s_addc_u32 s11, s11, 0
	s_waitcnt lgkmcnt(4)
	global_store_dwordx4 v75, v[192:195], s[10:11]
	s_add_u32 s10, s10, s16
	s_addc_u32 s11, s11, 0
	s_waitcnt lgkmcnt(3)
	global_store_dwordx4 v75, v[212:215], s[10:11]
	s_add_u32 s10, s10, s16
	s_addc_u32 s11, s11, 0
	s_waitcnt lgkmcnt(2)
	global_store_dwordx4 v75, v[216:219], s[10:11]
	s_add_u32 s10, s10, s16
	s_addc_u32 s11, s11, 0
	s_waitcnt lgkmcnt(1)
	global_store_dwordx4 v75, v[220:223], s[10:11]
	s_add_u32 s10, s10, s16
	s_addc_u32 s11, s11, 0
	s_waitcnt lgkmcnt(0)
	global_store_dwordx4 v75, v[224:227], s[10:11]
	s_branch .LBB0_173
.Lep_orig:
	s_lshl_b32 s15, s44, 1
	v_ashrrev_i32_e32 v71, 6, v73
	v_and_or_b32 v68, v71, 1, s15
	s_ashr_i32 s14, s0, 6
	v_cmp_lt_i32_e32 vcc, 3, v68
	s_and_saveexec_b64 s[6:7], vcc
	s_xor_b64 s[6:7], exec, s[6:7]
	s_cbranch_execz .LBB0_248
	s_cmp_gt_u32 s15, 7
	s_mov_b64 s[12:13], -1
	s_cbranch_scc0 .LBB0_245
	s_cmp_gt_u32 s15, 11
	s_cbranch_scc0 .LBB0_242
	s_cmp_gt_u32 s15, 15
	s_cbranch_scc0 .LBB0_239
	s_cmp_gt_u32 s15, 23
	s_cbranch_scc0 .LBB0_236
	s_cmp_gt_u32 s15, 25
	s_cbranch_scc0 .LBB0_233
	s_cmp_gt_u32 s15, 27
	s_cbranch_scc0 .LBB0_230
	s_cmp_gt_u32 s15, 29
	s_cbranch_scc0 .LBB0_227
	s_cmp_gt_u32 s15, 31
	s_cbranch_scc0 .LBB0_224
	s_cmp_gt_u32 s15, 33
	s_mov_b64 s[4:5], -1
	s_cbranch_scc0 .LBB0_222
	s_cmp_gt_u32 s15, 35
	s_cbranch_scc0 .LBB0_219
	s_cmp_gt_u32 s15, 43
	s_cbranch_scc0 .LBB0_216
	s_cmp_gt_u32 s15, 47
	s_cbranch_scc0 .LBB0_213
	s_mov_b64 s[84:85], -1
	s_cmp_gt_u32 s15, 51
	s_cbranch_scc0 .LBB0_210
	s_cmp_gt_u32 s15, 55
	s_cbranch_scc0 .LBB0_207
	s_cmp_gt_u32 s15, 59
	s_cbranch_scc0 .LBB0_204
	v_cmp_eq_u32_e64 s[10:11], 60, v68
	s_mov_b64 s[4:5], 0
